# attention: K/V/Q/old-output loads made system-coherent (sc1) and the L1/L2 invalidate after the flags gate dropped
# baseline (speedup 1.0000x reference)
.LBB0_138:
	v_cmp_eq_u32_e32 vcc, 0, v218
	s_and_saveexec_b64 s[4:5], vcc
	s_cbranch_execz .LBB0_140
	s_waitcnt vmcnt(0)
	s_nop 0
	s_waitcnt vmcnt(0)

.LBB0_142:
	s_add_u32 s4, s0, 0x4a00000
	s_addc_u32 s5, s1, 0
	s_and_b32 s12, s86, 15
	s_bfe_u32 s18, s86, 0x40004
	s_and_b64 s[10:11], s[8:9], exec
	s_cselect_b32 s13, 2, 0
	s_and_b64 s[10:11], s[6:7], exec
	s_cselect_b32 s10, 4, s13
	v_writelane_b32 v254, s60, 63
	s_lshr_b32 s28, s12, s10
	s_lshl_b32 s30, s18, 6
	v_writelane_b32 v255, s61, 0
	v_writelane_b32 v255, s10, 1
	s_lshl_b32 s10, s28, s10
	s_sub_i32 s22, s12, s10
	s_lshl_b32 s10, s86, 4
	s_and_b32 s20, s10, 0xfffff000
	s_lshl_b32 s21, s22, 8
	s_or_b32 s24, s20, s28
	s_waitcnt vmcnt(0)
	v_ashrrev_i32_e32 v162, 3, v234
	s_and_b64 s[8:9], s[8:9], exec
	v_add_u32_e32 v163, 0xffffff80, v162
	s_cselect_b32 s8, 2, 4
	s_and_b64 s[6:7], s[6:7], exec
	v_add_u32_e32 v1, s21, v163
	s_cselect_b32 s43, 0, s8
	v_and_b32_e32 v2, 7, v233
	v_lshlrev_b32_e32 v3, s43, v1
	v_writelane_b32 v255, s8, 2
	v_lshlrev_b32_e32 v164, 3, v2
	v_cmp_lt_i32_e32 vcc, -1, v1
	v_add_lshl_u32 v3, v3, s24, 10
	s_and_saveexec_b64 s[6:7], vcc
	s_cbranch_execz .LBB0_144
	v_or3_b32 v4, v3, v164, s30
	v_mov_b32_e32 v5, v0
	v_lshl_add_u64 v[4:5], v[4:5], 1, s[4:5]
	global_load_dwordx4 v[82:85], v[4:5], off sc1
.LBB0_144:
	s_or_b64 exec, exec, s[6:7]
	v_add_u32_e32 v4, 64, v1
	s_movk_i32 s6, 0xffbf
	v_lshlrev_b32_e32 v4, s43, v4
	v_cmp_lt_i32_e64 s[6:7], s6, v1
	v_add_lshl_u32 v4, v4, s24, 10
	s_and_saveexec_b64 s[8:9], s[6:7]
	s_cbranch_execz .LBB0_146
	v_or3_b32 v6, v4, v164, s30
	v_mov_b32_e32 v7, v0
	v_lshl_add_u64 v[6:7], v[6:7], 1, s[4:5]
	global_load_dwordx4 v[86:89], v[6:7], off sc1
.LBB0_146:
	s_or_b64 exec, exec, s[8:9]
	v_add_u32_e32 v5, s21, v162
	v_cmp_lt_i32_e64 s[8:9], -1, v5
	v_lshlrev_b32_e32 v5, s43, v5
	v_add_lshl_u32 v5, v5, s24, 10
	s_and_saveexec_b64 s[10:11], s[8:9]
	s_cbranch_execz .LBB0_148
	v_or3_b32 v6, v5, v164, s30
	v_mov_b32_e32 v7, v0
	v_lshl_add_u64 v[6:7], v[6:7], 1, s[4:5]
	global_load_dwordx4 v[90:93], v[6:7], off sc1
.LBB0_148:
	s_or_b64 exec, exec, s[10:11]
	v_add_u32_e32 v6, 0xc0, v1
	s_movk_i32 s10, 0xff3f
	v_lshlrev_b32_e32 v6, s43, v6
	v_cmp_lt_i32_e64 s[10:11], s10, v1
	v_add_lshl_u32 v6, v6, s24, 10
	s_and_saveexec_b64 s[12:13], s[10:11]
	s_cbranch_execz .LBB0_150
	v_or3_b32 v8, v6, v164, s30
	v_mov_b32_e32 v9, v0
	v_lshl_add_u64 v[8:9], v[8:9], 1, s[4:5]
	global_load_dwordx4 v[94:97], v[8:9], off sc1
.LBB0_150:
	s_or_b64 exec, exec, s[12:13]
	v_add_u32_e32 v7, 0x100, v1
	s_movk_i32 s12, 0xfeff
	v_lshlrev_b32_e32 v7, s43, v7
	v_cmp_lt_i32_e64 s[12:13], s12, v1
	v_add_lshl_u32 v7, v7, s24, 10
	s_and_saveexec_b64 s[14:15], s[12:13]
	s_cbranch_execz .LBB0_152
	v_or3_b32 v8, v7, v164, s30
	v_mov_b32_e32 v9, v0
	v_lshl_add_u64 v[8:9], v[8:9], 1, s[4:5]
	global_load_dwordx4 v[98:101], v[8:9], off sc1
.LBB0_152:
	s_or_b64 exec, exec, s[14:15]
	v_add_u32_e32 v8, 0x140, v1
	s_movk_i32 s14, 0xfebf
	v_cmp_lt_i32_e64 s[14:15], s14, v1
	v_lshlrev_b32_e32 v1, s43, v8
	v_add_lshl_u32 v8, v1, s24, 10
	s_and_saveexec_b64 s[16:17], s[14:15]
	s_cbranch_execz .LBB0_154
	v_or3_b32 v10, v8, v164, s30
	v_mov_b32_e32 v11, v0
	v_lshl_add_u64 v[10:11], v[10:11], 1, s[4:5]
	global_load_dwordx4 v[102:105], v[10:11], off sc1
.LBB0_154:
	s_or_b64 exec, exec, s[16:17]
	s_add_u32 s94, s0, 0x6a00000
	s_addc_u32 s95, s1, 0
	s_add_u32 s26, s0, 0x8a00000
	s_addc_u32 s27, s1, 0
	s_ashr_i32 s19, s19, 6
	s_lshl_b32 s23, s19, 5
	v_and_b32_e32 v165, 31, v233
	s_add_i32 s16, s23, s21
	v_or_b32_e32 v9, s16, v165
	v_lshrrev_b32_e32 v1, 5, v218
	v_lshlrev_b32_e32 v9, s43, v9
	v_add_lshl_u32 v9, v9, s24, 10
	v_lshlrev_b32_e32 v166, 3, v1
	v_or3_b32 v10, v9, v166, s30
	v_mov_b32_e32 v11, v0
	v_writelane_b32 v255, s26, 3
	s_nop 1
	v_lshl_add_u64 v[10:11], v[10:11], 1, s[26:27]
	global_load_dwordx4 v[130:133], v[10:11], off sc1
	global_load_dwordx4 v[134:137], v[10:11], off offset:32 sc1
	global_load_dwordx4 v[138:141], v[10:11], off offset:64 sc1
	global_load_dwordx4 v[142:145], v[10:11], off offset:96 sc1
	v_writelane_b32 v255, s27, 4
	s_and_saveexec_b64 s[16:17], vcc
	s_cbranch_execz .LBB0_231
	v_or3_b32 v10, v3, v164, s30
	v_mov_b32_e32 v11, v0
	v_lshl_add_u64 v[10:11], v[10:11], 1, s[94:95]
	global_load_dwordx4 v[106:109], v[10:11], off sc1
	s_or_b64 exec, exec, s[16:17]
	s_and_saveexec_b64 s[16:17], s[6:7]
	s_cbranch_execnz .LBB0_232

.LBB0_157:
	v_or3_b32 v4, v5, v164, s30
	v_mov_b32_e32 v5, v0
	v_lshl_add_u64 v[4:5], v[4:5], 1, s[94:95]
	global_load_dwordx4 v[114:117], v[4:5], off sc1
	s_or_b64 exec, exec, s[6:7]
	s_and_saveexec_b64 s[6:7], s[10:11]
	s_cbranch_execnz .LBB0_234

.LBB0_159:
	v_or3_b32 v4, v7, v164, s30
	v_mov_b32_e32 v5, v0
	v_lshl_add_u64 v[4:5], v[4:5], 1, s[94:95]
	global_load_dwordx4 v[122:125], v[4:5], off sc1
.LBB0_160:
	v_writelane_b32 v255, s86, 5
	s_or_b64 exec, exec, s[6:7]
	s_and_saveexec_b64 s[6:7], s[14:15]
	s_cbranch_execz .LBB0_162
	v_or3_b32 v4, v8, v164, s30
	v_mov_b32_e32 v5, v0
	v_lshl_add_u64 v[4:5], v[4:5], 1, s[94:95]
	global_load_dwordx4 v[126:129], v[4:5], off sc1

.LBB0_174:
	s_add_i32 s24, s26, s98
	s_cmpk_lt_i32 s24, 0x400
	s_cselect_b64 s[74:75], -1, 0
	s_cmpk_gt_i32 s24, 0x3ff
	s_cselect_b64 s[92:93], -1, 0
	s_and_b64 vcc, exec, s[92:93]
	s_cbranch_vccnz .LBB0_188
	s_and_b32 s21, s24, 15
	v_readlane_b32 s19, v255, 37
	s_lshr_b32 s19, s21, s19
	v_readlane_b32 s27, v255, 1
	s_lshl_b32 s27, s19, s27
	s_sub_i32 s27, s21, s27
	s_lshl_b32 s21, s24, 4
	s_lshl_b32 s34, s27, 8
	s_bfe_u32 s29, s24, 0x40004
	s_and_b32 s31, s21, 0xfffff000
	s_lshl_b32 s21, s29, 6
	s_or_b32 s35, s31, s19
	s_add_i32 s101, s43, 11
	v_lshlrev_b32_e32 v1, s101, v162
	s_add_i32 s100, s101, 8
	v_lshl_add_u32 v1, v164, 1, v1
	s_lshl_b32 s100, s27, s100
	s_lshl_b32 s72, s35, 11
	s_add_i32 s72, s72, s100
	s_lshl_b32 s100, s21, 1
	s_add_i32 s72, s72, s100
	s_add_i32 s100, s101, 6
	s_lshl_b32 s100, 1, s100
	s_add_u32 s72, s4, s72
	s_addc_u32 s73, s5, 0
	global_load_dwordx4 v[90:93], v1, s[72:73] sc1
	s_cmp_eq_u32 s27, 0
	s_cbranch_scc1 .Lk_skip01
	s_sub_u32 s72, s72, s100
	s_subb_u32 s73, s73, 0
	global_load_dwordx4 v[86:89], v1, s[72:73] sc1
	s_sub_u32 s72, s72, s100
	s_subb_u32 s73, s73, 0
	global_load_dwordx4 v[82:85], v1, s[72:73] sc1
	s_add_u32 s72, s72, s100
	s_addc_u32 s73, s73, 0
	s_add_u32 s72, s72, s100
	s_addc_u32 s73, s73, 0
.Lk_skip01:
	s_add_u32 s72, s72, s100
	s_addc_u32 s73, s73, 0
	global_load_dwordx4 v[94:97], v1, s[72:73] sc1
	s_add_u32 s72, s72, s100
	s_addc_u32 s73, s73, 0
	global_load_dwordx4 v[98:101], v1, s[72:73] sc1
	s_add_u32 s72, s72, s100
	s_addc_u32 s73, s73, 0
	global_load_dwordx4 v[102:105], v1, s[72:73] sc1
.LBB0_187:
	v_add_u32_e32 v1, s34, v179
	v_lshlrev_b32_e32 v1, s43, v1
	v_add_lshl_u32 v1, v1, s35, 10
	v_readlane_b32 s34, v255, 3
	v_or3_b32 v130, v1, v166, s21
	v_mov_b32_e32 v131, v0
	v_readlane_b32 s35, v255, 4
	s_nop 1
	v_lshl_add_u64 v[142:143], v[130:131], 1, s[34:35]
	global_load_dwordx4 v[130:133], v[142:143], off sc1
	global_load_dwordx4 v[134:137], v[142:143], off offset:32 sc1
	global_load_dwordx4 v[138:141], v[142:143], off offset:64 sc1
	s_nop 0
	global_load_dwordx4 v[142:145], v[142:143], off offset:96 sc1
	s_branch .LBB0_189

.LBB0_189:
	v_readlane_b32 s34, v255, 11
	v_readlane_b32 s35, v255, 12
	v_cndmask_b32_e64 v1, v50, v232, s[8:9]
	v_cndmask_b32_e64 v58, v58, v232, s[40:41]
	v_cndmask_b32_e64 v50, v66, v232, s[34:35]
	v_readlane_b32 s34, v255, 13
	v_readlane_b32 s35, v255, 14
	v_cndmask_b32_e64 v50, v50, v66, s[8:9]
	v_cndmask_b32_e64 v59, v59, v232, s[44:45]
	v_cndmask_b32_e64 v51, v51, v232, s[34:35]
	v_readlane_b32 s34, v255, 15
	v_readlane_b32 s35, v255, 16
	v_cndmask_b32_e64 v60, v60, v232, s[48:49]
	v_cndmask_b32_e64 v61, v61, v232, s[52:53]
	v_cndmask_b32_e64 v52, v52, v232, s[34:35]
	v_readlane_b32 s34, v255, 17
	v_readlane_b32 s35, v255, 18
	v_cndmask_b32_e64 v62, v62, v232, s[56:57]
	v_cndmask_b32_e64 v63, v63, v232, s[60:61]
	v_cndmask_b32_e64 v66, v68, v232, s[34:35]
	v_readlane_b32 s34, v255, 19
	v_readlane_b32 s35, v255, 20
	v_cndmask_b32_e64 v64, v64, v232, s[64:65]
	v_cndmask_b32_e64 v65, v65, v232, s[68:69]
	v_cndmask_b32_e64 v53, v53, v232, s[34:35]
	v_readlane_b32 s34, v255, 21
	v_readlane_b32 s35, v255, 22
	v_cndmask_b32_e64 v67, v232, v67, s[8:9]
	s_andn2_b64 vcc, exec, s[74:75]
	v_cndmask_b32_e64 v68, v69, v232, s[34:35]
	v_readlane_b32 s34, v255, 23
	v_readlane_b32 s35, v255, 24
	s_nop 1
	v_cndmask_b32_e64 v54, v54, v232, s[34:35]
	v_readlane_b32 s34, v255, 25
	v_readlane_b32 s35, v255, 26
	s_nop 1
	v_cndmask_b32_e64 v69, v70, v232, s[34:35]
	v_readlane_b32 s34, v255, 27
	v_readlane_b32 s35, v255, 28
	s_nop 1
	v_cndmask_b32_e64 v55, v55, v232, s[34:35]
	v_readlane_b32 s34, v255, 29
	v_readlane_b32 s35, v255, 30
	s_nop 1
	v_cndmask_b32_e64 v70, v71, v232, s[34:35]
	v_readlane_b32 s34, v255, 31
	v_readlane_b32 s35, v255, 32
	s_nop 1
	v_cndmask_b32_e64 v56, v56, v232, s[34:35]
	v_readlane_b32 s34, v255, 33
	v_readlane_b32 s35, v255, 34
	s_nop 1
	v_cndmask_b32_e64 v71, v72, v232, s[34:35]
	v_readlane_b32 s34, v255, 35
	v_readlane_b32 s35, v255, 36
	v_cndmask_b32_e64 v72, v73, v232, s[38:39]
	v_cndmask_b32_e64 v73, v74, v232, s[16:17]
	v_cndmask_b32_e64 v57, v57, v232, s[34:35]
	s_mov_b32 s34, 0xf149f2ca
	v_cndmask_b32_e64 v74, v75, v232, s[46:47]
	v_cndmask_b32_e64 v75, v76, v232, s[50:51]
	v_cndmask_b32_e64 v76, v77, v232, s[54:55]
	v_cndmask_b32_e64 v77, v78, v232, s[58:59]
	v_cndmask_b32_e64 v78, v79, v232, s[62:63]
	v_cndmask_b32_e64 v79, v80, v232, s[66:67]
	v_cndmask_b32_e64 v80, v81, v232, s[70:71]
	v_max3_f32 v81, v1, s34, v51
	v_max3_f32 v81, v81, v52, v53
	v_max3_f32 v81, v81, v54, v55
	v_max3_f32 v81, v81, v56, v57
	v_max3_f32 v81, v81, v58, v59
	v_max3_f32 v81, v81, v60, v61
	v_max3_f32 v81, v81, v62, v63
	v_max3_f32 v81, v81, v64, v65
	v_max3_f32 v81, v81, v2, v3
	v_max3_f32 v81, v81, v4, v5
	v_max3_f32 v81, v81, v6, v7
	v_max3_f32 v81, v81, v8, v9
	v_max3_f32 v81, v81, v10, v11
	v_max3_f32 v81, v81, v12, v13
	v_max3_f32 v81, v81, v14, v15
	v_max3_f32 v81, v81, v16, v17
	v_max3_f32 v81, v81, v34, v35
	v_max3_f32 v81, v81, v36, v37
	v_max3_f32 v81, v81, v38, v39
	v_max3_f32 v81, v81, v40, v41
	v_max3_f32 v81, v81, v42, v43
	v_max3_f32 v81, v81, v44, v45
	v_max3_f32 v81, v81, v46, v47
	v_max3_f32 v81, v81, v48, v49
	v_max3_f32 v81, v81, v18, v19
	v_max3_f32 v81, v81, v20, v21
	v_max3_f32 v81, v81, v22, v23
	v_max3_f32 v81, v81, v24, v25
	v_max3_f32 v81, v81, v26, v27
	v_max3_f32 v81, v81, v28, v29
	v_max3_f32 v81, v81, v30, v31
	v_max3_f32 v81, v81, v32, v33
	v_max3_f32 v81, v81, v50, v67
	v_max3_f32 v81, v81, v66, v68
	v_max3_f32 v81, v81, v69, v70
	v_max3_f32 v81, v81, v71, v72
	v_max3_f32 v81, v81, v73, v74
	v_max3_f32 v81, v81, v75, v76
	v_max3_f32 v81, v81, v77, v78
	v_max3_f32 v81, v81, v79, v80
	ds_bpermute_b32 v225, v180, v81
	s_waitcnt lgkmcnt(0)
	v_max_f32_e32 v225, v225, v225
	v_max_f32_e32 v81, v81, v225
	v_sub_f32_e32 v1, v1, v81
	v_exp_f32_e32 v1, v1
	v_sub_f32_e32 v51, v51, v81
	v_exp_f32_e32 v51, v51
	v_sub_f32_e32 v52, v52, v81
	v_exp_f32_e32 v52, v52
	v_sub_f32_e32 v53, v53, v81
	v_exp_f32_e32 v53, v53
	v_sub_f32_e32 v54, v54, v81
	v_add_f32_e32 v225, 0, v1
	v_exp_f32_e32 v54, v54
	v_sub_f32_e32 v55, v55, v81
	v_add_f32_e32 v225, v51, v225
	v_exp_f32_e32 v55, v55
	v_sub_f32_e32 v56, v56, v81
	v_add_f32_e32 v225, v52, v225
	v_exp_f32_e32 v56, v56
	v_sub_f32_e32 v57, v57, v81
	v_add_f32_e32 v225, v53, v225
	v_exp_f32_e32 v57, v57
	v_sub_f32_e32 v58, v58, v81
	v_add_f32_e32 v225, v54, v225
	v_exp_f32_e32 v58, v58
	v_sub_f32_e32 v59, v59, v81
	v_add_f32_e32 v225, v55, v225
	v_exp_f32_e32 v59, v59
	v_sub_f32_e32 v60, v60, v81
	v_add_f32_e32 v225, v56, v225
	v_exp_f32_e32 v60, v60
	v_sub_f32_e32 v61, v61, v81
	v_add_f32_e32 v225, v57, v225
	v_exp_f32_e32 v61, v61
	v_sub_f32_e32 v62, v62, v81
	v_add_f32_e32 v225, v58, v225
	v_exp_f32_e32 v62, v62
	v_sub_f32_e32 v63, v63, v81
	v_add_f32_e32 v225, v59, v225
	v_exp_f32_e32 v63, v63
	v_sub_f32_e32 v64, v64, v81
	v_add_f32_e32 v225, v60, v225
	v_exp_f32_e32 v64, v64
	v_sub_f32_e32 v65, v65, v81
	v_add_f32_e32 v225, v61, v225
	v_exp_f32_e32 v65, v65
	v_sub_f32_e32 v2, v2, v81
	v_add_f32_e32 v225, v62, v225
	v_exp_f32_e32 v230, v2
	v_sub_f32_e32 v2, v3, v81
	v_add_f32_e32 v225, v63, v225
	v_exp_f32_e32 v231, v2
	v_sub_f32_e32 v2, v4, v81
	v_add_f32_e32 v225, v64, v225
	v_exp_f32_e32 v237, v2
	v_sub_f32_e32 v2, v5, v81
	v_add_f32_e32 v225, v65, v225
	v_exp_f32_e32 v238, v2
	v_sub_f32_e32 v3, v6, v81
	v_add_f32_e32 v2, v230, v225
	v_exp_f32_e32 v225, v3
	v_sub_f32_e32 v3, v7, v81
	v_add_f32_e32 v2, v231, v2
	v_exp_f32_e32 v239, v3
	v_sub_f32_e32 v3, v8, v81
	v_add_f32_e32 v2, v237, v2
	v_exp_f32_e32 v240, v3
	v_sub_f32_e32 v3, v9, v81
	v_add_f32_e32 v2, v238, v2
	v_exp_f32_e32 v241, v3
	v_sub_f32_e32 v3, v10, v81
	v_add_f32_e32 v2, v225, v2
	v_exp_f32_e32 v10, v3
	v_sub_f32_e32 v3, v11, v81
	v_add_f32_e32 v2, v239, v2
	v_exp_f32_e32 v11, v3
	v_sub_f32_e32 v3, v12, v81
	v_add_f32_e32 v2, v240, v2
	v_exp_f32_e32 v12, v3
	v_sub_f32_e32 v3, v13, v81
	v_add_f32_e32 v2, v241, v2
	v_exp_f32_e32 v13, v3
	v_sub_f32_e32 v3, v14, v81
	v_add_f32_e32 v2, v10, v2
	v_exp_f32_e32 v14, v3
	v_sub_f32_e32 v3, v15, v81
	v_add_f32_e32 v2, v11, v2
	v_exp_f32_e32 v15, v3
	v_sub_f32_e32 v3, v16, v81
	v_add_f32_e32 v2, v12, v2
	v_exp_f32_e32 v16, v3
	v_sub_f32_e32 v3, v17, v81
	v_add_f32_e32 v2, v13, v2
	v_exp_f32_e32 v17, v3
	v_sub_f32_e32 v3, v34, v81
	v_add_f32_e32 v2, v14, v2
	v_exp_f32_e32 v34, v3
	v_sub_f32_e32 v3, v35, v81
	v_add_f32_e32 v2, v15, v2
	v_exp_f32_e32 v35, v3
	v_sub_f32_e32 v3, v36, v81
	v_add_f32_e32 v2, v16, v2
	v_exp_f32_e32 v36, v3
	v_sub_f32_e32 v3, v37, v81
	v_add_f32_e32 v2, v17, v2
	v_exp_f32_e32 v37, v3
	v_sub_f32_e32 v3, v38, v81
	v_add_f32_e32 v2, v34, v2
	v_exp_f32_e32 v38, v3
	v_sub_f32_e32 v3, v39, v81
	v_add_f32_e32 v2, v35, v2
	v_exp_f32_e32 v39, v3
	v_sub_f32_e32 v3, v40, v81
	v_add_f32_e32 v2, v36, v2
	v_exp_f32_e32 v40, v3
	v_sub_f32_e32 v3, v41, v81
	v_add_f32_e32 v2, v37, v2
	v_exp_f32_e32 v41, v3
	v_sub_f32_e32 v3, v42, v81
	v_add_f32_e32 v2, v38, v2
	v_exp_f32_e32 v42, v3
	v_sub_f32_e32 v3, v43, v81
	v_add_f32_e32 v2, v39, v2
	v_exp_f32_e32 v43, v3
	v_sub_f32_e32 v3, v44, v81
	v_add_f32_e32 v2, v40, v2
	v_exp_f32_e32 v44, v3
	v_sub_f32_e32 v3, v45, v81
	v_add_f32_e32 v2, v41, v2
	v_exp_f32_e32 v45, v3
	v_sub_f32_e32 v3, v46, v81
	v_add_f32_e32 v2, v42, v2
	v_exp_f32_e32 v46, v3
	v_sub_f32_e32 v3, v47, v81
	v_add_f32_e32 v2, v43, v2
	v_exp_f32_e32 v47, v3
	v_sub_f32_e32 v3, v48, v81
	v_add_f32_e32 v2, v44, v2
	v_exp_f32_e32 v48, v3
	v_sub_f32_e32 v3, v49, v81
	v_add_f32_e32 v2, v45, v2
	v_exp_f32_e32 v49, v3
	v_sub_f32_e32 v3, v18, v81
	v_add_f32_e32 v2, v46, v2
	v_exp_f32_e32 v18, v3
	v_sub_f32_e32 v3, v19, v81
	v_add_f32_e32 v2, v47, v2
	v_exp_f32_e32 v19, v3
	v_sub_f32_e32 v3, v20, v81
	v_add_f32_e32 v2, v48, v2
	v_exp_f32_e32 v20, v3
	v_sub_f32_e32 v3, v21, v81
	v_add_f32_e32 v2, v49, v2
	v_exp_f32_e32 v21, v3
	v_sub_f32_e32 v3, v22, v81
	v_add_f32_e32 v2, v18, v2
	v_exp_f32_e32 v22, v3
	v_sub_f32_e32 v3, v23, v81
	v_add_f32_e32 v2, v19, v2
	v_exp_f32_e32 v23, v3
	v_sub_f32_e32 v3, v24, v81
	v_add_f32_e32 v2, v20, v2
	v_exp_f32_e32 v24, v3
	v_sub_f32_e32 v3, v25, v81
	v_add_f32_e32 v2, v21, v2
	v_exp_f32_e32 v25, v3
	v_sub_f32_e32 v3, v26, v81
	v_add_f32_e32 v2, v22, v2
	v_exp_f32_e32 v26, v3
	v_sub_f32_e32 v3, v27, v81
	v_add_f32_e32 v2, v23, v2
	v_exp_f32_e32 v27, v3
	v_sub_f32_e32 v3, v28, v81
	v_add_f32_e32 v2, v24, v2
	v_exp_f32_e32 v28, v3
	v_sub_f32_e32 v3, v29, v81
	v_add_f32_e32 v2, v25, v2
	v_exp_f32_e32 v29, v3
	v_sub_f32_e32 v3, v30, v81
	v_add_f32_e32 v2, v26, v2
	v_exp_f32_e32 v30, v3
	v_sub_f32_e32 v3, v31, v81
	v_add_f32_e32 v2, v27, v2
	v_exp_f32_e32 v31, v3
	v_sub_f32_e32 v3, v32, v81
	v_add_f32_e32 v2, v28, v2
	v_exp_f32_e32 v32, v3
	v_sub_f32_e32 v3, v33, v81
	v_add_f32_e32 v2, v29, v2
	v_exp_f32_e32 v33, v3
	v_sub_f32_e32 v3, v50, v81
	v_add_f32_e32 v2, v30, v2
	v_exp_f32_e32 v50, v3
	v_sub_f32_e32 v3, v67, v81
	v_add_f32_e32 v2, v31, v2
	v_exp_f32_e32 v242, v3
	v_sub_f32_e32 v3, v66, v81
	v_add_f32_e32 v2, v32, v2
	v_exp_f32_e32 v243, v3
	v_sub_f32_e32 v3, v68, v81
	v_add_f32_e32 v2, v33, v2
	v_exp_f32_e32 v244, v3
	v_sub_f32_e32 v3, v69, v81
	v_add_f32_e32 v2, v50, v2
	v_exp_f32_e32 v245, v3
	v_sub_f32_e32 v3, v70, v81
	v_add_f32_e32 v2, v242, v2
	v_exp_f32_e32 v246, v3
	v_sub_f32_e32 v3, v71, v81
	v_add_f32_e32 v2, v243, v2
	v_exp_f32_e32 v247, v3
	v_sub_f32_e32 v3, v72, v81
	v_add_f32_e32 v2, v244, v2
	v_exp_f32_e32 v248, v3
	v_sub_f32_e32 v3, v73, v81
	v_add_f32_e32 v2, v245, v2
	v_exp_f32_e32 v249, v3
	v_sub_f32_e32 v3, v74, v81
	v_add_f32_e32 v2, v246, v2
	v_exp_f32_e32 v250, v3
	v_sub_f32_e32 v3, v75, v81
	v_add_f32_e32 v2, v247, v2
	v_exp_f32_e32 v251, v3
	v_sub_f32_e32 v3, v76, v81
	v_add_f32_e32 v2, v248, v2
	v_exp_f32_e32 v252, v3
	v_sub_f32_e32 v3, v77, v81
	v_add_f32_e32 v2, v249, v2
	v_exp_f32_e32 v253, v3
	v_sub_f32_e32 v3, v78, v81
	v_add_f32_e32 v2, v250, v2
	v_exp_f32_e32 v219, v3
	v_sub_f32_e32 v3, v79, v81
	v_add_f32_e32 v2, v251, v2
	v_exp_f32_e32 v229, v3
	v_sub_f32_e32 v3, v80, v81
	v_add_f32_e32 v2, v252, v2
	v_exp_f32_e32 v80, v3
	v_add_f32_e32 v2, v253, v2
	v_add_f32_e32 v2, v219, v2
	v_add_f32_e32 v2, v229, v2
	v_add_f32_e32 v235, v80, v2
	ds_bpermute_b32 v236, v180, v235
	v_cvt_pk_bf16_f32 v6, v1, v51
	v_cndmask_b32_e64 v1, 0, 1, s[74:75]
	v_cvt_pk_bf16_f32 v7, v52, v53
	v_cvt_pk_bf16_f32 v8, v54, v55
	v_cvt_pk_bf16_f32 v9, v56, v57
	v_cvt_pk_bf16_f32 v2, v58, v59
	v_cvt_pk_bf16_f32 v3, v60, v61
	v_cvt_pk_bf16_f32 v4, v62, v63
	v_cvt_pk_bf16_f32 v5, v64, v65
	v_cvt_pk_bf16_f32 v76, v230, v231
	v_cvt_pk_bf16_f32 v77, v237, v238
	v_cvt_pk_bf16_f32 v78, v225, v239
	v_cvt_pk_bf16_f32 v79, v240, v241
	v_cvt_pk_bf16_f32 v72, v10, v11
	v_cvt_pk_bf16_f32 v73, v12, v13
	v_cvt_pk_bf16_f32 v74, v14, v15
	v_cvt_pk_bf16_f32 v75, v16, v17
	v_cvt_pk_bf16_f32 v68, v34, v35
	v_cvt_pk_bf16_f32 v69, v36, v37
	v_cvt_pk_bf16_f32 v70, v38, v39
	v_cvt_pk_bf16_f32 v71, v40, v41
	v_cvt_pk_bf16_f32 v64, v42, v43
	v_cvt_pk_bf16_f32 v65, v44, v45
	v_cvt_pk_bf16_f32 v66, v46, v47
	v_cvt_pk_bf16_f32 v67, v48, v49
	v_cvt_pk_bf16_f32 v60, v18, v19
	v_cvt_pk_bf16_f32 v61, v20, v21
	v_cvt_pk_bf16_f32 v62, v22, v23
	v_cvt_pk_bf16_f32 v63, v24, v25
	v_cvt_pk_bf16_f32 v56, v26, v27
	v_cvt_pk_bf16_f32 v57, v28, v29
	v_cvt_pk_bf16_f32 v58, v30, v31
	v_cvt_pk_bf16_f32 v59, v32, v33
	v_cvt_pk_bf16_f32 v52, v50, v242
	v_cvt_pk_bf16_f32 v53, v243, v244
	v_cvt_pk_bf16_f32 v54, v245, v246
	v_cvt_pk_bf16_f32 v55, v247, v248
	v_cvt_pk_bf16_f32 v48, v249, v250
	v_cvt_pk_bf16_f32 v49, v251, v252
	v_cvt_pk_bf16_f32 v50, v253, v219
	v_cvt_pk_bf16_f32 v51, v229, v80
	v_cmp_ne_u32_e64 s[72:73], 1, v1
	s_cbranch_vccnz .LBB0_203
	s_add_i32 s101, s43, 11
	v_lshlrev_b32_e32 v10, s101, v162
	s_add_i32 s100, s101, 8
	v_lshl_add_u32 v10, v164, 1, v10
	s_lshl_b32 s100, s27, s100
	s_add_i32 s74, s19, s31
	s_lshl_b32 s74, s74, 11
	s_add_i32 s74, s74, s100
	s_lshl_b32 s100, s21, 1
	s_add_i32 s74, s74, s100
	s_add_i32 s100, s101, 6
	s_lshl_b32 s100, 1, s100
	s_add_u32 s74, s94, s74
	s_addc_u32 s75, s95, 0
	global_load_dwordx4 v[114:117], v10, s[74:75] sc1
	s_cmp_eq_u32 s27, 0
	s_cbranch_scc1 .Lv_skip01
	s_sub_u32 s74, s74, s100
	s_subb_u32 s75, s75, 0
	global_load_dwordx4 v[110:113], v10, s[74:75] sc1
	s_sub_u32 s74, s74, s100
	s_subb_u32 s75, s75, 0
	global_load_dwordx4 v[106:109], v10, s[74:75] sc1
	s_add_u32 s74, s74, s100
	s_addc_u32 s75, s75, 0
	s_add_u32 s74, s74, s100
	s_addc_u32 s75, s75, 0
.Lv_skip01:
	s_add_u32 s74, s74, s100
	s_addc_u32 s75, s75, 0
	global_load_dwordx4 v[118:121], v10, s[74:75] sc1
	s_add_u32 s74, s74, s100
	s_addc_u32 s75, s75, 0
	global_load_dwordx4 v[122:125], v10, s[74:75] sc1
	s_add_u32 s74, s74, s100
	s_addc_u32 s75, s75, 0
	global_load_dwordx4 v[126:129], v10, s[74:75] sc1
.LBB0_203:
	v_cndmask_b32_e64 v1, 0, 1, s[86:87]
	v_cmp_ne_u32_e64 s[74:75], 1, v1
	v_or_b32_e32 v1, s25, v181
	s_andn2_b64 vcc, exec, s[86:87]
	v_add_u32_e32 v80, s30, v182
	v_lshlrev_b32_e32 v225, s43, v1
	s_cbranch_vccnz .LBB0_206
	s_add_i32 s34, s28, s20
	v_or_b32_e32 v14, s25, v165
	v_readlane_b32 s100, v254, 54
	v_lshlrev_b32_e32 v14, s43, v14
	v_readlane_b32 s101, v254, 55
	v_add_u32_e32 v14, s34, v14
	v_lshl_add_u32 v14, v14, 4, s18
	v_mov_b32_e32 v15, v0
	v_lshl_add_u64 v[14:15], v[14:15], 2, s[100:101]
	global_load_dword v237, v[14:15], off sc1
	v_or_b32_e32 v12, 8, v1
	v_add_u32_e32 v10, s34, v225
	v_lshlrev_b32_e32 v12, s43, v12
	v_lshl_add_u32 v10, v10, 10, v80
	v_mov_b32_e32 v11, v0
	v_add_u32_e32 v12, s34, v12
	v_lshl_add_u64 v[10:11], v[10:11], 1, s[88:89]
	v_lshl_add_u32 v12, v12, 10, v80
	v_mov_b32_e32 v13, v0
	v_lshl_add_u64 v[12:13], v[12:13], 1, s[88:89]
	global_load_dwordx4 v[150:153], v[10:11], off sc1
	global_load_dwordx4 v[146:149], v[12:13], off sc1
	v_or_b32_e32 v10, 16, v1
	v_or_b32_e32 v1, 24, v1
	v_lshlrev_b32_e32 v1, s43, v1
	v_lshlrev_b32_e32 v10, s43, v10
	v_add_u32_e32 v1, s34, v1
	v_add_u32_e32 v10, s34, v10
	v_lshl_add_u32 v12, v1, 10, v80
	v_lshl_add_u32 v10, v10, 10, v80
	v_mov_b32_e32 v11, v0
	v_lshl_add_u64 v[10:11], v[10:11], 1, s[88:89]
	v_mov_b32_e32 v13, v0
	v_lshl_add_u64 v[12:13], v[12:13], 1, s[88:89]
	global_load_dwordx4 v[158:161], v[10:11], off sc1
	global_load_dwordx4 v[154:157], v[12:13], off sc1
	s_andn2_b64 vcc, exec, s[76:77]
	s_cbranch_vccnz .LBB0_207

.LBB0_232:
	v_or3_b32 v10, v4, v164, s30
	v_mov_b32_e32 v11, v0
	v_lshl_add_u64 v[10:11], v[10:11], 1, s[94:95]
	global_load_dwordx4 v[110:113], v[10:11], off sc1
	s_or_b64 exec, exec, s[16:17]
	s_and_saveexec_b64 s[6:7], s[8:9]
	s_cbranch_execnz .LBB0_157

.LBB0_234:
	v_or3_b32 v4, v6, v164, s30
	v_mov_b32_e32 v5, v0
	v_lshl_add_u64 v[4:5], v[4:5], 1, s[94:95]
	global_load_dwordx4 v[118:121], v[4:5], off sc1
	s_or_b64 exec, exec, s[6:7]
	s_and_saveexec_b64 s[6:7], s[12:13]
	s_cbranch_execnz .LBB0_159
	s_branch .LBB0_160

.LBB0_287:
	s_ashr_i32 s21, s20, 31
	s_lshl_b64 s[22:23], s[20:21], 19
	s_add_u32 s22, s80, s22
	s_addc_u32 s23, s81, s23
	s_and_b64 s[24:25], s[6:7], exec
	s_cselect_b32 s21, s23, s29
	s_cselect_b32 s36, s22, s28
	s_ashr_i32 s19, s18, 31
	s_lshl_b64 s[24:25], s[18:19], 19
	s_add_u32 s24, s40, s24
	s_addc_u32 s25, s41, s25
	s_and_b64 s[34:35], s[6:7], exec
	s_cselect_b32 s19, s25, s31
	s_cselect_b32 s37, s24, s30
	s_add_u32 s38, s30, 0x100
	s_addc_u32 s39, s31, 0
	s_add_u32 s28, s28, 0x40080
	s_addc_u32 s29, s29, 0
	s_mov_b32 s55, -2
	s_add_u32 s30, s28, 0xfffc0080
	s_addc_u32 s31, s29, -1
	s_add_i32 s56, 0, 0x10000
	s_cmp_eq_u32 s55, 12
	s_cselect_b32 s35, s21, s31
	s_cselect_b32 s34, s36, s30
	s_cselect_b32 s31, s19, s39
	s_cselect_b32 s30, s37, s38
	s_add_i32 s58, 0, 0x14000
	v_add_u32_e32 v166, s56, v147
	v_add_u32_e32 v182, s58, v147
	ds_read_b128 v[142:145], v166
	ds_read_b128 v[158:161], v166 offset:1024
	ds_read_b128 v[162:165], v166 offset:2048
	ds_read_b128 v[166:169], v166 offset:3072
	ds_read_b128 v[170:173], v182
	ds_read_b128 v[174:177], v182 offset:1024
	ds_read_b128 v[178:181], v182 offset:2048
	ds_read_b128 v[182:185], v182 offset:3072
	v_lshl_add_u64 v[224:225], s[28:29], 0, v[140:141]
	s_add_i32 m0, s44, 0xc000
	ds_read_b128 v[186:189], v157
	ds_read_b128 v[190:193], v157 offset:1024
	ds_read_b128 v[194:197], v157 offset:2048
	ds_read_b128 v[198:201], v157 offset:3072
	ds_read_b128 v[202:205], v157 offset:4096
	ds_read_b128 v[206:209], v157 offset:5120
	ds_read_b128 v[220:223], v157 offset:6144
	ds_read_b128 v[236:239], v157 offset:7168
	global_load_lds_dwordx4 v[224:225], off
	v_lshl_add_u64 v[224:225], s[28:29], 0, v[138:139]
	s_add_i32 m0, s44, 0xe000
	s_nop 0
	global_load_lds_dwordx4 v[224:225], off
	s_nop 0
	s_nop 0
	s_nop 0
	s_nop 0
	s_nop 0
	s_nop 0
	s_nop 0
	s_nop 0
	s_nop 0
	s_nop 0
	s_nop 0
	s_nop 0
	s_nop 0
	s_nop 0
	s_nop 0
	s_nop 0
	s_nop 0
	s_nop 0
	s_nop 0
	s_nop 0
	s_waitcnt vmcnt(8)
	s_waitcnt lgkmcnt(0)
	s_barrier
	s_waitcnt lgkmcnt(0)
	v_mfma_f32_16x16x32_bf16 v[126:129], v[142:145], v[186:189], 0
	v_mfma_f32_16x16x32_bf16 v[122:125], v[162:165], v[186:189], 0
	v_mfma_f32_16x16x32_bf16 v[110:113], v[142:145], v[194:197], 0
	v_mfma_f32_16x16x32_bf16 v[106:109], v[162:165], v[194:197], 0
	v_mfma_f32_16x16x32_bf16 v[94:97], v[142:145], v[202:205], 0
	v_mfma_f32_16x16x32_bf16 v[90:93], v[162:165], v[202:205], 0
	v_mfma_f32_16x16x32_bf16 v[78:81], v[142:145], v[220:223], 0
	v_mfma_f32_16x16x32_bf16 v[74:77], v[162:165], v[220:223], 0
	v_mfma_f32_16x16x32_bf16 v[126:129], v[158:161], v[190:193], v[126:129]
	v_mfma_f32_16x16x32_bf16 v[122:125], v[166:169], v[190:193], v[122:125]
	v_mfma_f32_16x16x32_bf16 v[110:113], v[158:161], v[198:201], v[110:113]
	v_mfma_f32_16x16x32_bf16 v[106:109], v[166:169], v[198:201], v[106:109]
	v_mfma_f32_16x16x32_bf16 v[94:97], v[158:161], v[206:209], v[94:97]
	v_mfma_f32_16x16x32_bf16 v[90:93], v[166:169], v[206:209], v[90:93]
	v_mfma_f32_16x16x32_bf16 v[78:81], v[158:161], v[236:239], v[78:81]
	v_mfma_f32_16x16x32_bf16 v[74:77], v[166:169], v[236:239], v[74:77]
	v_mfma_f32_16x16x32_bf16 v[118:121], v[170:173], v[186:189], 0
	v_mfma_f32_16x16x32_bf16 v[114:117], v[178:181], v[186:189], 0
	v_mfma_f32_16x16x32_bf16 v[102:105], v[170:173], v[194:197], 0
	v_mfma_f32_16x16x32_bf16 v[98:101], v[178:181], v[194:197], 0
	v_mfma_f32_16x16x32_bf16 v[86:89], v[170:173], v[202:205], 0
	v_mfma_f32_16x16x32_bf16 v[82:85], v[178:181], v[202:205], 0
	v_mfma_f32_16x16x32_bf16 v[70:73], v[170:173], v[220:223], 0
	v_mfma_f32_16x16x32_bf16 v[66:69], v[178:181], v[220:223], 0
	v_mfma_f32_16x16x32_bf16 v[118:121], v[174:177], v[190:193], v[118:121]
	v_mfma_f32_16x16x32_bf16 v[114:117], v[182:185], v[190:193], v[114:117]
	v_mfma_f32_16x16x32_bf16 v[102:105], v[174:177], v[198:201], v[102:105]
	v_mfma_f32_16x16x32_bf16 v[98:101], v[182:185], v[198:201], v[98:101]
	v_mfma_f32_16x16x32_bf16 v[86:89], v[174:177], v[206:209], v[86:89]
	v_mfma_f32_16x16x32_bf16 v[82:85], v[182:185], v[206:209], v[82:85]
	v_mfma_f32_16x16x32_bf16 v[70:73], v[174:177], v[236:239], v[70:73]
	v_mfma_f32_16x16x32_bf16 v[66:69], v[182:185], v[236:239], v[66:69]
	s_barrier
	s_add_i32 s56, s56, s27
	v_lshl_add_u64 v[224:225], s[30:31], 0, v[132:133]
	s_mov_b32 m0, s56
	ds_read_b128 v[186:189], v157 offset:16384
	ds_read_b128 v[190:193], v157 offset:17408
	ds_read_b128 v[194:197], v157 offset:18432
	ds_read_b128 v[198:201], v157 offset:19456
	ds_read_b128 v[202:205], v157 offset:20480
	ds_read_b128 v[206:209], v157 offset:21504
	ds_read_b128 v[220:223], v157 offset:22528
	ds_read_b128 v[236:239], v157 offset:23552
	global_load_lds_dwordx4 v[224:225], off
	s_add_i32 m0, s56, 0x2000
	s_add_u32 s56, s30, 0x40000
	v_lshl_add_u64 v[230:231], s[30:31], 0, v[136:137]
	s_addc_u32 s57, s31, 0
	s_add_i32 s58, s58, s27
	global_load_lds_dwordx4 v[230:231], off
	v_lshl_add_u64 v[240:241], s[56:57], 0, v[132:133]
	s_mov_b32 m0, s58
	v_lshl_add_u64 v[242:243], s[34:35], 0, v[134:135]
	global_load_lds_dwordx4 v[240:241], off
	v_lshl_add_u64 v[240:241], s[56:57], 0, v[136:137]
	s_add_i32 m0, s58, 0x2000
	s_nop 0
	global_load_lds_dwordx4 v[240:241], off
	v_lshl_add_u64 v[240:241], s[34:35], 0, v[130:131]
	s_mov_b32 m0, s44
	s_nop 0
	global_load_lds_dwordx4 v[240:241], off
	s_mov_b32 m0, s45
	s_nop 0
	global_load_lds_dwordx4 v[242:243], off
	s_nop 0
	s_nop 0
	s_nop 0
	s_waitcnt vmcnt(8)
	s_waitcnt lgkmcnt(0)
	s_barrier
	s_waitcnt lgkmcnt(0)
	v_mfma_f32_16x16x32_bf16 v[62:65], v[142:145], v[186:189], 0
	v_mfma_f32_16x16x32_bf16 v[58:61], v[162:165], v[186:189], 0
	v_mfma_f32_16x16x32_bf16 v[46:49], v[142:145], v[194:197], 0
	v_mfma_f32_16x16x32_bf16 v[42:45], v[162:165], v[194:197], 0
	v_mfma_f32_16x16x32_bf16 v[30:33], v[142:145], v[202:205], 0
	v_mfma_f32_16x16x32_bf16 v[26:29], v[162:165], v[202:205], 0
	v_mfma_f32_16x16x32_bf16 v[14:17], v[142:145], v[220:223], 0
	v_mfma_f32_16x16x32_bf16 v[10:13], v[162:165], v[220:223], 0
	v_mfma_f32_16x16x32_bf16 v[62:65], v[158:161], v[190:193], v[62:65]
	v_mfma_f32_16x16x32_bf16 v[58:61], v[166:169], v[190:193], v[58:61]
	v_mfma_f32_16x16x32_bf16 v[46:49], v[158:161], v[198:201], v[46:49]
	v_mfma_f32_16x16x32_bf16 v[42:45], v[166:169], v[198:201], v[42:45]
	v_mfma_f32_16x16x32_bf16 v[30:33], v[158:161], v[206:209], v[30:33]
	v_mfma_f32_16x16x32_bf16 v[26:29], v[166:169], v[206:209], v[26:29]
	v_mfma_f32_16x16x32_bf16 v[14:17], v[158:161], v[236:239], v[14:17]
	v_mfma_f32_16x16x32_bf16 v[10:13], v[166:169], v[236:239], v[10:13]
	v_mfma_f32_16x16x32_bf16 v[54:57], v[170:173], v[186:189], 0
	v_mfma_f32_16x16x32_bf16 v[50:53], v[178:181], v[186:189], 0
	v_mfma_f32_16x16x32_bf16 v[38:41], v[170:173], v[194:197], 0
	v_mfma_f32_16x16x32_bf16 v[34:37], v[178:181], v[194:197], 0
	v_mfma_f32_16x16x32_bf16 v[22:25], v[170:173], v[202:205], 0
	v_mfma_f32_16x16x32_bf16 v[18:21], v[178:181], v[202:205], 0
	v_mfma_f32_16x16x32_bf16 v[6:9], v[170:173], v[220:223], 0
	v_mfma_f32_16x16x32_bf16 v[2:5], v[178:181], v[220:223], 0
	v_mfma_f32_16x16x32_bf16 v[54:57], v[174:177], v[190:193], v[54:57]
	v_mfma_f32_16x16x32_bf16 v[50:53], v[182:185], v[190:193], v[50:53]
	v_mfma_f32_16x16x32_bf16 v[38:41], v[174:177], v[198:201], v[38:41]
	v_mfma_f32_16x16x32_bf16 v[34:37], v[182:185], v[198:201], v[34:37]
	v_mfma_f32_16x16x32_bf16 v[22:25], v[174:177], v[206:209], v[22:25]
	v_mfma_f32_16x16x32_bf16 v[18:21], v[182:185], v[206:209], v[18:21]
	v_mfma_f32_16x16x32_bf16 v[6:9], v[174:177], v[236:239], v[6:9]
	v_mfma_f32_16x16x32_bf16 v[2:5], v[182:185], v[236:239], v[2:5]
	s_barrier
	s_add_i32 s56, 0, 0x18000
	s_add_i32 s57, 0, 0x1c000
	v_add_u32_e32 v166, s56, v147
	v_add_u32_e32 v182, s57, v147
	ds_read_b128 v[142:145], v166
	ds_read_b128 v[158:161], v166 offset:1024
	ds_read_b128 v[162:165], v166 offset:2048
	ds_read_b128 v[166:169], v166 offset:3072
	ds_read_b128 v[170:173], v182
	ds_read_b128 v[174:177], v182 offset:1024
	ds_read_b128 v[178:181], v182 offset:2048
	ds_read_b128 v[182:185], v182 offset:3072
	s_add_u32 s34, s34, 0x40000
	s_addc_u32 s35, s35, 0
	s_mov_b32 m0, s43
	v_lshl_add_u64 v[244:245], s[34:35], 0, v[130:131]
	ds_read_b128 v[186:189], v157 offset:32768
	ds_read_b128 v[190:193], v157 offset:33792
	ds_read_b128 v[194:197], v157 offset:34816
	ds_read_b128 v[198:201], v157 offset:35840
	ds_read_b128 v[202:205], v157 offset:36864
	ds_read_b128 v[206:209], v157 offset:37888
	ds_read_b128 v[220:223], v157 offset:38912
	ds_read_b128 v[236:239], v157 offset:39936
	global_load_lds_dwordx4 v[244:245], off
	v_lshl_add_u64 v[244:245], s[34:35], 0, v[134:135]
	s_mov_b32 m0, s46
	s_nop 0
	global_load_lds_dwordx4 v[244:245], off
	s_nop 0
	s_nop 0
	s_nop 0
	s_nop 0
	s_nop 0
	s_nop 0
	s_nop 0
	s_waitcnt vmcnt(8)
	s_waitcnt lgkmcnt(0)
	s_barrier
	s_waitcnt lgkmcnt(0)
	v_mfma_f32_16x16x32_bf16 v[126:129], v[142:145], v[186:189], v[126:129]
	v_mfma_f32_16x16x32_bf16 v[122:125], v[162:165], v[186:189], v[122:125]
	v_mfma_f32_16x16x32_bf16 v[110:113], v[142:145], v[194:197], v[110:113]
	v_mfma_f32_16x16x32_bf16 v[106:109], v[162:165], v[194:197], v[106:109]
	v_mfma_f32_16x16x32_bf16 v[94:97], v[142:145], v[202:205], v[94:97]
	v_mfma_f32_16x16x32_bf16 v[90:93], v[162:165], v[202:205], v[90:93]
	v_mfma_f32_16x16x32_bf16 v[78:81], v[142:145], v[220:223], v[78:81]
	v_mfma_f32_16x16x32_bf16 v[74:77], v[162:165], v[220:223], v[74:77]
	v_mfma_f32_16x16x32_bf16 v[126:129], v[158:161], v[190:193], v[126:129]
	v_mfma_f32_16x16x32_bf16 v[122:125], v[166:169], v[190:193], v[122:125]
	v_mfma_f32_16x16x32_bf16 v[110:113], v[158:161], v[198:201], v[110:113]
	v_mfma_f32_16x16x32_bf16 v[106:109], v[166:169], v[198:201], v[106:109]
	v_mfma_f32_16x16x32_bf16 v[94:97], v[158:161], v[206:209], v[94:97]
	v_mfma_f32_16x16x32_bf16 v[90:93], v[166:169], v[206:209], v[90:93]
	v_mfma_f32_16x16x32_bf16 v[78:81], v[158:161], v[236:239], v[78:81]
	v_mfma_f32_16x16x32_bf16 v[74:77], v[166:169], v[236:239], v[74:77]
	v_mfma_f32_16x16x32_bf16 v[118:121], v[170:173], v[186:189], v[118:121]
	v_mfma_f32_16x16x32_bf16 v[114:117], v[178:181], v[186:189], v[114:117]
	v_mfma_f32_16x16x32_bf16 v[102:105], v[170:173], v[194:197], v[102:105]
	v_mfma_f32_16x16x32_bf16 v[98:101], v[178:181], v[194:197], v[98:101]
	v_mfma_f32_16x16x32_bf16 v[86:89], v[170:173], v[202:205], v[86:89]
	v_mfma_f32_16x16x32_bf16 v[82:85], v[178:181], v[202:205], v[82:85]
	v_mfma_f32_16x16x32_bf16 v[70:73], v[170:173], v[220:223], v[70:73]
	v_mfma_f32_16x16x32_bf16 v[66:69], v[178:181], v[220:223], v[66:69]
	v_mfma_f32_16x16x32_bf16 v[118:121], v[174:177], v[190:193], v[118:121]
	v_mfma_f32_16x16x32_bf16 v[114:117], v[182:185], v[190:193], v[114:117]
	v_mfma_f32_16x16x32_bf16 v[102:105], v[174:177], v[198:201], v[102:105]
	v_mfma_f32_16x16x32_bf16 v[98:101], v[182:185], v[198:201], v[98:101]
	v_mfma_f32_16x16x32_bf16 v[86:89], v[174:177], v[206:209], v[86:89]
	v_mfma_f32_16x16x32_bf16 v[82:85], v[182:185], v[206:209], v[82:85]
	v_mfma_f32_16x16x32_bf16 v[70:73], v[174:177], v[236:239], v[70:73]
	v_mfma_f32_16x16x32_bf16 v[66:69], v[182:185], v[236:239], v[66:69]
	s_barrier
	s_add_i32 s34, s56, s27
	v_lshl_add_u64 v[224:225], v[224:225], 0, s[96:97]
	s_mov_b32 m0, s34
	ds_read_b128 v[186:189], v157 offset:49152
	ds_read_b128 v[190:193], v157 offset:50176
	ds_read_b128 v[194:197], v157 offset:51200
	ds_read_b128 v[198:201], v157 offset:52224
	ds_read_b128 v[202:205], v157 offset:53248
	ds_read_b128 v[206:209], v157 offset:54272
	ds_read_b128 v[220:223], v157 offset:55296
	ds_read_b128 v[236:239], v157 offset:56320
	global_load_lds_dwordx4 v[224:225], off
	s_add_i32 m0, s34, 0x2000
	s_add_u32 s30, s30, 0x40080
	v_lshl_add_u64 v[224:225], v[230:231], 0, s[96:97]
	s_addc_u32 s31, s31, 0
	s_add_i32 s34, s57, s27
	global_load_lds_dwordx4 v[224:225], off
	v_lshl_add_u64 v[224:225], s[30:31], 0, v[132:133]
	s_mov_b32 m0, s34
	s_nop 0
	global_load_lds_dwordx4 v[224:225], off
	v_lshl_add_u64 v[224:225], s[30:31], 0, v[136:137]
	s_add_i32 m0, s34, 0x2000
	s_nop 0
	global_load_lds_dwordx4 v[224:225], off
	v_lshl_add_u64 v[224:225], v[240:241], 0, s[96:97]
	s_mov_b32 m0, s47
	s_nop 0
	global_load_lds_dwordx4 v[224:225], off
	v_lshl_add_u64 v[224:225], v[242:243], 0, s[96:97]
	s_mov_b32 m0, s48
	s_nop 0
	global_load_lds_dwordx4 v[224:225], off
	s_nop 0
	s_nop 0
	s_waitcnt vmcnt(8)
	s_waitcnt lgkmcnt(0)
	s_barrier
	s_waitcnt lgkmcnt(0)
	v_mfma_f32_16x16x32_bf16 v[62:65], v[142:145], v[186:189], v[62:65]
	v_mfma_f32_16x16x32_bf16 v[58:61], v[162:165], v[186:189], v[58:61]
	v_mfma_f32_16x16x32_bf16 v[46:49], v[142:145], v[194:197], v[46:49]
	v_mfma_f32_16x16x32_bf16 v[42:45], v[162:165], v[194:197], v[42:45]
	v_mfma_f32_16x16x32_bf16 v[30:33], v[142:145], v[202:205], v[30:33]
	v_mfma_f32_16x16x32_bf16 v[26:29], v[162:165], v[202:205], v[26:29]
	v_mfma_f32_16x16x32_bf16 v[14:17], v[142:145], v[220:223], v[14:17]
	v_mfma_f32_16x16x32_bf16 v[10:13], v[162:165], v[220:223], v[10:13]
	v_mfma_f32_16x16x32_bf16 v[62:65], v[158:161], v[190:193], v[62:65]
	v_mfma_f32_16x16x32_bf16 v[58:61], v[166:169], v[190:193], v[58:61]
	v_mfma_f32_16x16x32_bf16 v[46:49], v[158:161], v[198:201], v[46:49]
	v_mfma_f32_16x16x32_bf16 v[42:45], v[166:169], v[198:201], v[42:45]
	v_mfma_f32_16x16x32_bf16 v[30:33], v[158:161], v[206:209], v[30:33]
	v_mfma_f32_16x16x32_bf16 v[26:29], v[166:169], v[206:209], v[26:29]
	v_mfma_f32_16x16x32_bf16 v[14:17], v[158:161], v[236:239], v[14:17]
	v_mfma_f32_16x16x32_bf16 v[10:13], v[166:169], v[236:239], v[10:13]
	v_mfma_f32_16x16x32_bf16 v[54:57], v[170:173], v[186:189], v[54:57]
	v_mfma_f32_16x16x32_bf16 v[50:53], v[178:181], v[186:189], v[50:53]
	v_mfma_f32_16x16x32_bf16 v[38:41], v[170:173], v[194:197], v[38:41]
	v_mfma_f32_16x16x32_bf16 v[34:37], v[178:181], v[194:197], v[34:37]
	v_mfma_f32_16x16x32_bf16 v[22:25], v[170:173], v[202:205], v[22:25]
	v_mfma_f32_16x16x32_bf16 v[18:21], v[178:181], v[202:205], v[18:21]
	v_mfma_f32_16x16x32_bf16 v[6:9], v[170:173], v[220:223], v[6:9]
	v_mfma_f32_16x16x32_bf16 v[2:5], v[178:181], v[220:223], v[2:5]
	v_mfma_f32_16x16x32_bf16 v[54:57], v[174:177], v[190:193], v[54:57]
	v_mfma_f32_16x16x32_bf16 v[50:53], v[182:185], v[190:193], v[50:53]
	v_mfma_f32_16x16x32_bf16 v[38:41], v[174:177], v[198:201], v[38:41]
	v_mfma_f32_16x16x32_bf16 v[34:37], v[182:185], v[198:201], v[34:37]
	v_mfma_f32_16x16x32_bf16 v[22:25], v[174:177], v[206:209], v[22:25]
	v_mfma_f32_16x16x32_bf16 v[18:21], v[182:185], v[206:209], v[18:21]
	v_mfma_f32_16x16x32_bf16 v[6:9], v[174:177], v[236:239], v[6:9]
	v_mfma_f32_16x16x32_bf16 v[2:5], v[182:185], v[236:239], v[2:5]
	s_barrier
	s_add_i32 s55, s55, 2
	s_add_u32 s38, s38, 0x100
	s_addc_u32 s39, s39, 0
	s_add_u32 s28, s28, 0x100
	s_addc_u32 s29, s29, 0
	s_cmp_gt_u32 s55, 13
